# accumulator zeroing via broadcast LDS reads, merged adjacent lgkm waits in SSD loop
# baseline (speedup 1.0000x reference)
; #define LAS __attribute__((address_space(3)))
; __global__ void __launch_bounds__(512, 2) fwd_megakernel(Params p) {
;     ...
;     unsigned* barw = (unsigned*)(p.ws + WS_BAR);
;     volatile LAS unsigned* bst = (volatile LAS unsigned*)(LAS uchar*)(smem + LDS_MAIN);
;     if (threadIdx.x == 0) { bst[0] = 0u; bst[1] = 0u; }
;     if (p.ph_hi - p.ph_lo > 1 && blockIdx.x == 0) for (int i = threadIdx.x; i < XCD_BAR_WORDS; i += 512) barw[i] = 0u;
;     __syncthreads();
;     XcdBarrier xb; xb.bar = barw; xb.x = 0u; xb.st = bst;
.LBB0_2:
	s_or_b64 exec, exec, s[2:3]
	v_mov_b32_e32 v10, 0x20010
	v_mov_b32_e32 v12, 0
	v_mov_b32_e32 v13, 0
	v_mov_b32_e32 v14, 0
	v_mov_b32_e32 v15, 0
	ds_write_b128 v10, v[12:15]
	s_load_dwordx16 s[76:91], s[0:1], 0x0
	s_sub_i32 s2, s93, s92
	s_cmp_lt_i32 s2, 2
	s_cselect_b64 s[2:3], -1, 0
	s_cmp_lg_u32 s68, 0
	s_waitcnt lgkmcnt(0)
	v_writelane_b32 v254, s76, 12
	s_cselect_b64 s[4:5], -1, 0
	s_or_b64 s[2:3], s[4:5], s[2:3]
	v_writelane_b32 v254, s77, 13
	v_writelane_b32 v254, s78, 14
	v_writelane_b32 v254, s79, 15
	v_writelane_b32 v254, s80, 16
	v_writelane_b32 v254, s81, 17
	v_writelane_b32 v254, s82, 18
	v_writelane_b32 v254, s83, 19
	v_writelane_b32 v254, s84, 20
	v_writelane_b32 v254, s85, 21
	v_writelane_b32 v254, s86, 22
	v_writelane_b32 v254, s87, 23
	v_writelane_b32 v254, s88, 24
	v_writelane_b32 v254, s89, 25
	v_writelane_b32 v254, s90, 26
	v_writelane_b32 v254, s91, 27
	s_and_b64 vcc, exec, s[2:3]
	s_cbranch_vccnz .LBB0_10
	v_sub_u32_e32 v1, 0xd7f, v136
	v_lshrrev_b32_e32 v2, 9, v1
	v_add_u32_e32 v1, 2, v2
	v_add_u32_e32 v137, 0x200, v136
	s_mov_b32 s2, 0
	v_and_b32_e32 v3, 14, v1
	v_mov_b32_e32 v1, v2
	s_mov_b32 s3, 1
	s_mov_b64 s[6:7], 0
	v_mov_b32_e32 v5, 0
	s_mov_b32 s8, s2
	v_mov_b64_e32 v[6:7], v[136:137]
	s_branch .LBB0_5

; template <class Epi, bool ALIGN_EPI = PG8_ALIGN, bool SP2 = PG8_SP2>
; __device__ __forceinline__ void gemm_phase(LAS uchar* lds, const Gemm g, const StaticOrder& S, const Epi& E) {
;     ...
;     f32x4 acc[2][2][4][2];
; #pragma unroll
;     for (int a = 0; a < 2; ++a)
; #pragma unroll
;         for (int b = 0; b < 2; ++b)
; #pragma unroll
;             for (int m = 0; m < 4; ++m)
; #pragma unroll
;                 for (int n = 0; n < 2; ++n) acc[a][b][m][n] = (f32x4){0.f, 0.f, 0.f, 0.f};
.LBB0_344:
	s_add_u32 s38, s4, 0x100
	v_mov_b32_e32 v129, 0x20010
	s_addc_u32 s39, s5, 0
	s_mov_b32 s40, -2
	ds_read_b128 v[2:5], v129
	ds_read_b128 v[6:9], v129
	ds_read_b128 v[10:13], v129
	ds_read_b128 v[14:17], v129
	ds_read_b128 v[18:21], v129
	ds_read_b128 v[22:25], v129
	ds_read_b128 v[26:29], v129
	ds_read_b128 v[30:33], v129
	ds_read_b128 v[34:37], v129
	ds_read_b128 v[38:41], v129
	ds_read_b128 v[42:45], v129
	ds_read_b128 v[46:49], v129
	ds_read_b128 v[50:53], v129
	ds_read_b128 v[54:57], v129
	ds_read_b128 v[58:61], v129
	ds_read_b128 v[62:65], v129
	ds_read_b128 v[66:69], v129
	ds_read_b128 v[70:73], v129
	ds_read_b128 v[74:77], v129
	ds_read_b128 v[78:81], v129
	ds_read_b128 v[82:85], v129
	ds_read_b128 v[86:89], v129
	ds_read_b128 v[90:93], v129
	ds_read_b128 v[94:97], v129
	ds_read_b128 v[98:101], v129
	ds_read_b128 v[102:105], v129
	ds_read_b128 v[106:109], v129
	ds_read_b128 v[110:113], v129
	ds_read_b128 v[114:117], v129
	ds_read_b128 v[118:121], v129
	ds_read_b128 v[122:125], v129
	ds_read_b128 v[126:129], v129

; __device__ __forceinline__ void phase_ssd(const Params& p, uchar* sm, int j, bf16_t* zx, const float* dtraw, float* ssqb) {
;     ...
;             if (c + 1 < 32) { const bf16_t* zb = zc + 64 * LDZ;
;                 load_raw(zb + 2048 + colx, toff, false, 2 * lp, rx); }
;             const u32x4 z0 = *(const u32x4*)(zc + colx + toff), z1 = *(const u32x4*)(zc + colx + LDZ + toff);
;             __syncthreads();
;             if (tabw) {
;                 const float v = dtr + dtb;
;                 const float dt = v > 20.f ? v : log1pf(__expf(v));
;                 const float cs = wave_incl_scan(dt * a_coef);
;                 const float c63 = __int_as_float(__builtin_amdgcn_readlane(__float_as_int(cs), 63));
;                 dtL[th * 64 + lane] = dt; csL[th * 64 + lane] = cs; e1L[th * 64 + lane] = __expf(cs); e2L[th * 64 + lane] = dt * __expf(c63 - cs);
;                 if (c + 1 < 32) dtr = dtraw[(zrow0 + 64 + lane) * 32 + headA + th];
;             } else {
;                 const int lt = w >> 1, st0 = (w & 1) * 2;
;                 f32x4 cacc[2] = {(f32x4){0.f, 0.f, 0.f, 0.f}, (f32x4){0.f, 0.f, 0.f, 0.f}};
; #pragma unroll
;                 for (int ks = 0; ks < 4; ++ks) {
;                     const bf16x8 a = *(const bf16x8*)(sm + L_C + (lt * 16 + l15) * RS_CB + (ks * 32 + quad * 8) * 2);
; #pragma unroll
;                     for (int q = 0; q < 2; ++q) { const bf16x8 b = *(const bf16x8*)(sm + L_B + ((st0 + q) * 16 + l15) * RS_CB + (ks * 32 + quad * 8) * 2);
;                         cacc[q] = __builtin_amdgcn_mfma_f32_16x16x32_bf16(a, b, cacc[q], 0, 0, 0); }
;                 }
; #pragma unroll
;                 for (int q = 0; q < 2; ++q)
; #pragma unroll
;                     for (int r = 0; r < 4; ++r) *(float*)(sm + L_CB + (lt * 16 + quad * 4 + r) * RS_CB + ((st0 + q) * 16 + l15) * 4) = cacc[q][r];
.LBB0_468:
	v_add_co_u32_e32 v96, vcc, 0x641c000, v104
	s_nop 1
	v_addc_co_u32_e32 v97, vcc, 0, v105, vcc
	v_add_co_u32_e32 v98, vcc, 0x641f000, v104
	s_nop 1
	v_addc_co_u32_e32 v99, vcc, 0, v105, vcc
	global_load_dwordx4 v[100:103], v[96:97], off
	s_nop 0
	global_load_dwordx4 v[96:99], v[98:99], off offset:128
	s_waitcnt lgkmcnt(0)
	s_barrier
	s_and_saveexec_b64 s[4:5], s[8:9]
	s_xor_b64 s[4:5], exec, s[4:5]
	s_cbranch_execz .LBB0_470
	ds_read_b128 v[106:109], v209
	ds_read_b128 v[110:113], v210 offset:17408
	ds_read_b128 v[114:117], v211 offset:17408
	ds_read_b128 v[122:125], v209 offset:64
	ds_read_b128 v[118:121], v210 offset:17472
	ds_read_b128 v[126:129], v211 offset:17472
	ds_read_b128 v[130:133], v209 offset:128
	ds_read_b128 v[178:181], v210 offset:17536
	ds_read_b128 v[238:241], v211 offset:17536
	s_waitcnt lgkmcnt(6)
	v_mfma_f32_16x16x32_bf16 v[110:113], v[106:109], v[110:113], 0
	v_mfma_f32_16x16x32_bf16 v[106:109], v[106:109], v[114:117], 0
	ds_read_b128 v[114:117], v209 offset:192
	ds_read_b128 v[242:245], v210 offset:17600
	s_waitcnt lgkmcnt(6)
	v_mfma_f32_16x16x32_bf16 v[110:113], v[122:125], v[118:121], v[110:113]
	ds_read_b128 v[118:121], v211 offset:17600
	s_waitcnt lgkmcnt(3)
	v_mfma_f32_16x16x32_bf16 v[106:109], v[122:125], v[126:129], v[106:109]
	v_mfma_f32_16x16x32_bf16 v[110:113], v[130:133], v[178:181], v[110:113]
	v_mfma_f32_16x16x32_bf16 v[106:109], v[130:133], v[238:241], v[106:109]
	s_waitcnt lgkmcnt(0)
	v_mfma_f32_16x16x32_bf16 v[110:113], v[114:117], v[242:245], v[110:113]
	v_mfma_f32_16x16x32_bf16 v[106:109], v[114:117], v[118:121], v[106:109]
	s_nop 4
	s_nop 1
	ds_write2_b32 v212, v110, v111 offset1:68
	ds_write2_b32 v212, v112, v113 offset0:136 offset1:204
	s_nop 0
	ds_write2_b32 v213, v106, v107 offset1:68
	ds_write2_b32 v213, v108, v109 offset0:136 offset1:204

; __device__ __forceinline__ unsigned pk2(float lo, float hi) { unsigned r; asm("v_cvt_pk_bf16_f32 %0, %1, %2" : "=v"(r) : "v"(lo), "v"(hi)); return r; }
; __device__ __forceinline__ void phase_ssd(const Params& p, uchar* sm, int j, bf16_t* zx, const float* dtraw, float* ssqb) {
;     ...
;             __syncthreads();
;             {
;                 const int mq = w & 3; const int l = mq * 16 + l15; const float csl = csL[rl * 64 + l];
; #pragma unroll
;                 for (int ks = 0; ks < 2; ++ks) {
;                     if (ks == 1 && mq < 2) continue;
;                     const f32x4 s0 = *(const f32x4*)(csL + rl * 64 + ks * 32 + quad * 8), s1 = *(const f32x4*)(csL + rl * 64 + ks * 32 + quad * 8 + 4);
;                     const f32x4 c0 = *(const f32x4*)(sm + L_CB + l * RS_CB + (ks * 32 + quad * 8) * 4), c1 = *(const f32x4*)(sm + L_CB + l * RS_CB + (ks * 32 + quad * 8 + 4) * 4);
;                     float mv[8];
; #pragma unroll
;                     for (int i = 0; i < 4; ++i) { const int sc = ks * 32 + quad * 8 + i;
;                         mv[i] = (sc <= l) ? c0[i] * __expf(csl - s0[i]) : 0.f;
;                         mv[4 + i] = (sc + 4 <= l) ? c1[i] * __expf(csl - s1[i]) : 0.f; }
;                     *(u32x4*)(sm + LDS_MM + (rl * 64 + l) * RS_T + (ks * 32 + quad * 8) * 2) = pack8(mv);
;                 }
;             }
;             f32x4 yacc[4];
;             {
;                 uchar* stw = sm + L_ST + w * (16 * RS_CB);
; #pragma unroll
;                 for (int n = 0; n < 8; ++n) { u32x2 o; o.x = pk2(st[n][0], st[n][1]); o.y = pk2(st[n][2], st[n][3]);
;                     *(u32x2*)(stw + l15 * RS_CB + (n * 16 + quad * 4) * 2) = o; }
; #pragma unroll
;                 for (int m = 0; m < 4; ++m) yacc[m] = (f32x4){0.f, 0.f, 0.f, 0.f};
; #pragma unroll
;                 for (int ks = 0; ks < 4; ++ks) {
;                     const bf16x8 bfr = *(const bf16x8*)(stw + l15 * RS_CB + (ks * 32 + quad * 8) * 2);
; #pragma unroll
;                     for (int m = 0; m < 4; ++m) { const bf16x8 afr = *(const bf16x8*)(sm + L_C + (m * 16 + l15) * RS_CB + (ks * 32 + quad * 8) * 2);
;                         yacc[m] = __builtin_amdgcn_mfma_f32_16x16x32_bf16(afr, bfr, yacc[m], 0, 0, 0); }
;                 }
.LBB0_475:
	s_or_b64 exec, exec, s[4:5]
	s_mov_b64 s[4:5], 0x641c000
	v_lshl_add_u64 v[180:181], v[104:105], 0, s[4:5]
	s_mov_b64 s[4:5], 0x641f080
	v_lshl_add_u64 v[178:179], v[104:105], 0, s[4:5]
	s_waitcnt lgkmcnt(0)
	s_barrier
	ds_read_b32 v104, v193
	ds_read_b128 v[106:109], v196
	ds_read_b128 v[110:113], v196 offset:16
	v_add_u32_e32 v105, v197, v195
	ds_read_b128 v[114:117], v105
	ds_read_b128 v[118:121], v105 offset:16
	s_waitcnt lgkmcnt(2)
	v_sub_f32_e32 v105, v104, v106
	v_sub_f32_e32 v106, v104, v110
	v_mul_f32_e32 v106, 0x3fb8aa3b, v106
	v_sub_f32_e32 v107, v104, v107
	v_sub_f32_e32 v110, v104, v111
	v_exp_f32_e32 v106, v106
	v_mul_f32_e32 v107, 0x3fb8aa3b, v107
	v_mul_f32_e32 v110, 0x3fb8aa3b, v110
	v_exp_f32_e32 v107, v107
	v_exp_f32_e32 v110, v110
	s_waitcnt lgkmcnt(0)
	v_mul_f32_e32 v106, v118, v106
	v_cndmask_b32_e64 v111, v106, 0, s[28:29]
	v_mul_f32_e32 v106, v115, v107
	v_mul_f32_e32 v107, v119, v110
	v_sub_f32_e32 v108, v104, v108
	v_sub_f32_e32 v110, v104, v112
	v_mul_f32_e32 v108, 0x3fb8aa3b, v108
	v_mul_f32_e32 v110, 0x3fb8aa3b, v110
	v_exp_f32_e32 v108, v108
	v_exp_f32_e32 v110, v110
	v_mul_f32_e32 v105, 0x3fb8aa3b, v105
	v_cndmask_b32_e64 v112, v107, 0, s[34:35]
	v_mul_f32_e32 v107, v116, v108
	v_mul_f32_e32 v108, v120, v110
	v_sub_f32_e32 v109, v104, v109
	v_sub_f32_e32 v110, v104, v113
	v_exp_f32_e32 v105, v105
	v_mul_f32_e32 v109, 0x3fb8aa3b, v109
	v_mul_f32_e32 v110, 0x3fb8aa3b, v110
	v_exp_f32_e32 v109, v109
	v_exp_f32_e32 v110, v110
	v_mul_f32_e32 v105, v114, v105
	v_cndmask_b32_e64 v105, v105, 0, s[26:27]
	v_cndmask_b32_e64 v106, 0, v106, s[30:31]
	v_cndmask_b32_e64 v113, v108, 0, s[38:39]
	v_mul_f32_e32 v108, v117, v109
	v_mul_f32_e32 v109, v121, v110
	v_cndmask_b32_e64 v107, v107, 0, s[36:37]
	v_cndmask_b32_e64 v108, v108, 0, s[40:41]
	v_cndmask_b32_e64 v109, v109, 0, s[42:43]
	v_cvt_pk_bf16_f32 v106, v105, v106
	v_add_u32_e32 v105, v198, v188
	v_cvt_pk_bf16_f32 v107, v107, v108
	v_cvt_pk_bf16_f32 v108, v111, v112
	v_cvt_pk_bf16_f32 v109, v113, v109
	ds_write_b128 v105, v[106:109]
	s_and_saveexec_b64 s[4:5], s[22:23]
	s_cbranch_execz .LBB0_477
	ds_read_b128 v[106:109], v196 offset:128
	ds_read_b128 v[110:113], v196 offset:144
	ds_read_b128 v[114:117], v214
	ds_read_b128 v[118:121], v214 offset:16
	s_waitcnt lgkmcnt(2)
	v_sub_f32_e32 v105, v104, v106
	v_sub_f32_e32 v106, v104, v110
	v_sub_f32_e32 v107, v104, v107
	v_mul_f32_e32 v105, 0x3fb8aa3b, v105
	v_mul_f32_e32 v106, 0x3fb8aa3b, v106
	v_mul_f32_e32 v107, 0x3fb8aa3b, v107
	v_sub_f32_e32 v110, v104, v111
	v_sub_f32_e32 v108, v104, v108
	v_sub_f32_e32 v111, v104, v112
	v_sub_f32_e32 v109, v104, v109
	v_sub_f32_e32 v104, v104, v113
	v_exp_f32_e32 v105, v105
	v_exp_f32_e32 v106, v106
	v_exp_f32_e32 v107, v107
	v_mul_f32_e32 v110, 0x3fb8aa3b, v110
	v_mul_f32_e32 v108, 0x3fb8aa3b, v108
	v_mul_f32_e32 v111, 0x3fb8aa3b, v111
	v_mul_f32_e32 v109, 0x3fb8aa3b, v109
	v_mul_f32_e32 v104, 0x3fb8aa3b, v104
	v_exp_f32_e32 v110, v110
	v_exp_f32_e32 v108, v108
	v_exp_f32_e32 v111, v111
	v_exp_f32_e32 v109, v109
	v_exp_f32_e32 v104, v104
	s_waitcnt lgkmcnt(0)
	v_mul_f32_e32 v105, v114, v105
	v_mul_f32_e32 v106, v118, v106
	v_mul_f32_e32 v107, v115, v107
	v_cndmask_b32_e64 v105, v105, 0, s[44:45]
	v_cndmask_b32_e64 v106, v106, 0, s[46:47]
	v_cndmask_b32_e64 v107, v107, 0, s[48:49]
	v_mul_f32_e32 v110, v119, v110
	v_mul_f32_e32 v108, v116, v108
	v_mul_f32_e32 v111, v120, v111
	v_mul_f32_e32 v109, v117, v109
	v_mul_f32_e32 v104, v121, v104
	v_cndmask_b32_e64 v110, v110, 0, s[50:51]
	v_cndmask_b32_e64 v108, v108, 0, s[52:53]
	v_cndmask_b32_e64 v111, v111, 0, s[54:55]
	v_cndmask_b32_e64 v109, v109, 0, s[56:57]
	v_cndmask_b32_e64 v112, v104, 0, s[58:59]
	v_cvt_pk_bf16_f32 v104, v105, v107
	v_cvt_pk_bf16_f32 v105, v108, v109
	v_cvt_pk_bf16_f32 v106, v106, v110
	v_cvt_pk_bf16_f32 v107, v111, v112
	ds_write_b128 v215, v[104:107]
.LBB0_477:
	s_or_b64 exec, exec, s[4:5]
	v_cvt_pk_bf16_f32 v104, v72, v73
	v_cvt_pk_bf16_f32 v105, v74, v75
	v_add_u32_e32 v108, v200, v194
	v_cvt_pk_bf16_f32 v106, v76, v77
	v_cvt_pk_bf16_f32 v107, v78, v79
	ds_write2_b64 v108, v[104:105], v[106:107] offset1:4
	v_cvt_pk_bf16_f32 v104, v64, v65
	v_cvt_pk_bf16_f32 v105, v66, v67
	v_cvt_pk_bf16_f32 v106, v68, v69
	v_cvt_pk_bf16_f32 v107, v70, v71
	ds_write2_b64 v108, v[104:105], v[106:107] offset0:8 offset1:12
	v_cvt_pk_bf16_f32 v104, v92, v93
	v_cvt_pk_bf16_f32 v105, v94, v95
	v_cvt_pk_bf16_f32 v106, v80, v81
	v_cvt_pk_bf16_f32 v107, v82, v83
	ds_write2_b64 v108, v[104:105], v[106:107] offset0:16 offset1:20
	v_cvt_pk_bf16_f32 v104, v84, v85
	v_cvt_pk_bf16_f32 v105, v86, v87
	v_cvt_pk_bf16_f32 v106, v88, v89
	v_cvt_pk_bf16_f32 v107, v90, v91
	ds_write2_b64 v108, v[104:105], v[106:107] offset0:24 offset1:28
	v_add_u32_e32 v128, v200, v188
	ds_read_b128 v[104:107], v128
	v_add_u32_e32 v129, v204, v199
	ds_read_b128 v[108:111], v129
	ds_read_b128 v[112:115], v216
	ds_read_b128 v[116:119], v216 offset:4352
	ds_read_b128 v[120:123], v216 offset:8704
	ds_read_b128 v[132:135], v128 offset:64
	ds_read_b128 v[124:127], v129 offset:64
	ds_read_b128 v[240:243], v216 offset:64
	ds_read_b128 v[244:247], v216 offset:4416
	ds_read_b128 v[248:251], v216 offset:8768
	s_waitcnt lgkmcnt(7)
	v_mfma_f32_16x16x32_bf16 v[108:111], v[108:111], v[104:107], 0
	s_andn2_b64 vcc, exec, s[0:1]
	v_mfma_f32_16x16x32_bf16 v[112:115], v[112:115], v[104:107], 0
	s_waitcnt lgkmcnt(5)
	v_mfma_f32_16x16x32_bf16 v[116:119], v[116:119], v[104:107], 0
	v_mfma_f32_16x16x32_bf16 v[104:107], v[120:123], v[104:107], 0
	ds_read_b128 v[120:123], v128 offset:128
	s_waitcnt lgkmcnt(4)
; __device__ __forceinline__ void phase_ssd(const Params& p, uchar* sm, int j, bf16_t* zx, const float* dtraw, float* ssqb) {
;     ...
;                 for (int ks = 0; ks < 4; ++ks) {
;                     const bf16x8 bfr = *(const bf16x8*)(stw + l15 * RS_CB + (ks * 32 + quad * 8) * 2);
; #pragma unroll
;                     for (int m = 0; m < 4; ++m) { const bf16x8 afr = *(const bf16x8*)(sm + L_C + (m * 16 + l15) * RS_CB + (ks * 32 + quad * 8) * 2);
;                         yacc[m] = __builtin_amdgcn_mfma_f32_16x16x32_bf16(afr, bfr, yacc[m], 0, 0, 0); }
;                 }
; #pragma unroll
;                 for (int m = 0; m < 4; ++m) { const f32x4 ev = *(const f32x4*)(e1L + rl * 64 + m * 16 + quad * 4);
; #pragma unroll
;                     for (int r = 0; r < 4; ++r) yacc[m][r] *= ev[r]; }
;                 const float cs63 = csL[rl * 64 + 63];
;                 bf16x8 xdt[2], xdd[2];
; #pragma unroll
;                 for (int ks = 0; ks < 2; ++ks) {
;                     float xr[8]; unpack8(*(const u32x4*)(sm + L_XT + (chl + l15) * RS_T + (((ks * 16 + quad * 4) ^ (4 * w)) * 4)), xr);
;                     const f32x4 d0 = *(const f32x4*)(dtL + rl * 64 + ks * 32 + quad * 8), d1 = *(const f32x4*)(dtL + rl * 64 + ks * 32 + quad * 8 + 4);
;                     const f32x4 g0 = *(const f32x4*)(e2L + rl * 64 + ks * 32 + quad * 8), g1 = *(const f32x4*)(e2L + rl * 64 + ks * 32 + quad * 8 + 4);
;                     float a[8], b[8];
; #pragma unroll
;                     for (int i = 0; i < 4; ++i) { a[i] = xr[i] * d0[i]; a[4 + i] = xr[4 + i] * d1[i]; b[i] = xr[i] * g0[i]; b[4 + i] = xr[4 + i] * g1[i]; }
;                     const u32x4 pa = pack8(a), pb = pack8(b);
;                     xdt[ks] = __builtin_bit_cast(bf16x8, pa); xdd[ks] = __builtin_bit_cast(bf16x8, pb);
;                 }
;                 __syncthreads();
; #pragma unroll
;                 for (int ks = 0; ks < 2; ++ks)
; #pragma unroll
;                     for (int m = 0; m < 4; ++m) {
;                         if (ks == 1 && m < 2) continue;
;                         const bf16x8 afr = *(const bf16x8*)(sm + LDS_MM + (rl * 64 + m * 16 + l15) * RS_T + (ks * 32 + quad * 8) * 2);
;                         yacc[m] = __builtin_amdgcn_mfma_f32_16x16x32_bf16(afr, xdt[ks], yacc[m], 0, 0, 0);
;                     }
;                 const float dec = e1L[rl * 64 + 63];
	v_mfma_f32_16x16x32_bf16 v[108:111], v[124:127], v[132:135], v[108:111]
	ds_read_b128 v[124:127], v129 offset:128
	s_waitcnt lgkmcnt(4)
	v_mfma_f32_16x16x32_bf16 v[112:115], v[240:243], v[132:135], v[112:115]
	ds_read_b128 v[240:243], v216 offset:128
	s_waitcnt lgkmcnt(4)
	v_mfma_f32_16x16x32_bf16 v[116:119], v[244:247], v[132:135], v[116:119]
	ds_read_b128 v[244:247], v216 offset:4480
	s_waitcnt lgkmcnt(4)
	v_mfma_f32_16x16x32_bf16 v[104:107], v[248:251], v[132:135], v[104:107]
	ds_read_b128 v[132:135], v216 offset:8832
	ds_read_b128 v[248:251], v128 offset:192
	s_waitcnt lgkmcnt(4)
	v_mfma_f32_16x16x32_bf16 v[108:111], v[124:127], v[120:123], v[108:111]
	ds_read_b128 v[124:127], v129 offset:192
	s_waitcnt lgkmcnt(4)
	v_mfma_f32_16x16x32_bf16 v[112:115], v[240:243], v[120:123], v[112:115]
	ds_read_b128 v[240:243], v216 offset:192
	s_waitcnt lgkmcnt(4)
	v_mfma_f32_16x16x32_bf16 v[116:119], v[244:247], v[120:123], v[116:119]
	ds_read_b128 v[244:247], v216 offset:4544
	s_waitcnt lgkmcnt(4)
	v_mfma_f32_16x16x32_bf16 v[104:107], v[132:135], v[120:123], v[104:107]
	ds_read_b128 v[128:131], v216 offset:8896
	ds_read_b128 v[120:123], v217
	ds_read_b128 v[132:135], v217 offset:64
	s_waitcnt lgkmcnt(5)
	v_mfma_f32_16x16x32_bf16 v[108:111], v[124:127], v[248:251], v[108:111]
	ds_read_b128 v[124:127], v217 offset:128
	s_waitcnt lgkmcnt(5)
	v_mfma_f32_16x16x32_bf16 v[112:115], v[240:243], v[248:251], v[112:115]
	ds_read_b128 v[240:243], v217 offset:192
	s_waitcnt lgkmcnt(4)
	v_mfma_f32_16x16x32_bf16 v[116:119], v[244:247], v[248:251], v[116:119]
	v_mfma_f32_16x16x32_bf16 v[104:107], v[128:131], v[248:251], v[104:107]
	ds_read_b128 v[248:251], v218 offset:53248
	s_waitcnt lgkmcnt(3)
	v_pk_mul_f32 v[110:111], v[110:111], v[122:123]
	s_nop 0
	v_pk_mul_f32 v[114:115], v[114:115], v[134:135]
	v_pk_mul_f32 v[112:113], v[112:113], v[132:133]
	v_pk_mul_f32 v[108:109], v[108:109], v[120:121]
	ds_read_b128 v[120:123], v201
	s_waitcnt lgkmcnt(3)
	v_pk_mul_f32 v[118:119], v[118:119], v[126:127]
	v_pk_mul_f32 v[116:117], v[116:117], v[124:125]
	ds_read_b128 v[124:127], v201 offset:16
	ds_read_b128 v[132:135], v202
	s_waitcnt lgkmcnt(4)
	v_pk_mul_f32 v[130:131], v[106:107], v[242:243]
	v_pk_mul_f32 v[128:129], v[104:105], v[240:241]
	ds_read_b128 v[238:241], v202 offset:16
	s_waitcnt lgkmcnt(4)
	v_lshlrev_b32_e32 v139, 16, v248
	v_and_b32_e32 v170, 0xffff0000, v248
	v_lshlrev_b32_e32 v237, 16, v249
	v_and_b32_e32 v242, 0xffff0000, v249
	v_lshlrev_b32_e32 v243, 16, v250
	v_and_b32_e32 v244, 0xffff0000, v250
	v_lshlrev_b32_e32 v245, 16, v251
	v_and_b32_e32 v246, 0xffff0000, v251
	s_waitcnt lgkmcnt(2)
	v_mul_f32_e32 v122, v122, v237
	v_mul_f32_e32 v124, v124, v243
	v_mul_f32_e32 v125, v125, v244
	v_mul_f32_e32 v126, v126, v245
	v_mul_f32_e32 v127, v127, v246
	s_waitcnt lgkmcnt(1)
	v_mul_f32_e32 v237, v134, v237
	v_mul_f32_e32 v123, v123, v242
	v_mul_f32_e32 v242, v135, v242
	v_cvt_pk_bf16_f32 v134, v124, v125
	v_cvt_pk_bf16_f32 v135, v126, v127
	ds_read_b128 v[124:127], v219 offset:53248
	v_mul_f32_e32 v120, v120, v139
	v_mul_f32_e32 v139, v132, v139
	s_waitcnt lgkmcnt(1)
	v_mul_f32_e32 v238, v238, v243
	v_mul_f32_e32 v121, v121, v170
	v_mul_f32_e32 v170, v133, v170
	v_mul_f32_e32 v239, v239, v244
	v_mul_f32_e32 v240, v240, v245
	v_mul_f32_e32 v241, v241, v246
	v_cvt_pk_bf16_f32 v132, v120, v121
	v_cvt_pk_bf16_f32 v133, v122, v123
	v_cvt_pk_bf16_f32 v104, v139, v170
	v_cvt_pk_bf16_f32 v105, v237, v242
	v_cvt_pk_bf16_f32 v106, v238, v239
	v_cvt_pk_bf16_f32 v107, v240, v241
	s_waitcnt lgkmcnt(0)
	v_lshlrev_b32_e32 v139, 16, v124
	v_and_b32_e32 v170, 0xffff0000, v124
	v_lshlrev_b32_e32 v237, 16, v125
	v_and_b32_e32 v250, 0xffff0000, v125
	v_lshlrev_b32_e32 v251, 16, v126
	v_and_b32_e32 v252, 0xffff0000, v126
	v_lshlrev_b32_e32 v253, 16, v127
	v_and_b32_e32 v182, 0xffff0000, v127
	ds_read_b128 v[124:127], v201 offset:128
	ds_read_b128 v[238:241], v201 offset:144
	ds_read_b128 v[242:245], v202 offset:128
	ds_read_b128 v[246:249], v202 offset:144
	s_waitcnt lgkmcnt(0)
	s_barrier
	ds_read_b128 v[120:123], v220
	s_waitcnt lgkmcnt(0)
	v_mfma_f32_16x16x32_bf16 v[108:111], v[120:123], v[132:135], v[108:111]
	ds_read_b128 v[120:123], v220 offset:2304
	v_mul_f32_e32 v241, v241, v182
	v_mul_f32_e32 v124, v124, v139
	s_waitcnt lgkmcnt(0)
	v_mfma_f32_16x16x32_bf16 v[112:115], v[120:123], v[132:135], v[112:115]
	ds_read_b128 v[120:123], v220 offset:4608
	v_mul_f32_e32 v144, v238, v251
	v_mul_f32_e32 v139, v242, v139
	s_waitcnt lgkmcnt(0)
	v_mfma_f32_16x16x32_bf16 v[116:119], v[120:123], v[132:135], v[116:119]
	ds_read_b128 v[120:123], v220 offset:6912
	v_mul_f32_e32 v145, v246, v251
	v_mul_f32_e32 v125, v125, v170
	s_waitcnt lgkmcnt(0)
	v_mfma_f32_16x16x32_bf16 v[128:131], v[120:123], v[132:135], v[128:131]
	ds_read_b128 v[120:123], v220 offset:4672
	v_mul_f32_e32 v242, v239, v252
	v_mul_f32_e32 v126, v126, v237
	v_mul_f32_e32 v246, v240, v253
	v_mul_f32_e32 v127, v127, v250
	v_cvt_pk_bf16_f32 v238, v124, v125
	v_cvt_pk_bf16_f32 v239, v126, v127
	v_cvt_pk_bf16_f32 v240, v144, v242
	v_cvt_pk_bf16_f32 v241, v246, v241
	v_mul_f32_e32 v170, v243, v170
	s_waitcnt lgkmcnt(0)
	v_mfma_f32_16x16x32_bf16 v[120:123], v[120:123], v[238:241], v[116:119]
	ds_read_b128 v[116:119], v220 offset:6976
	v_mul_f32_e32 v243, v247, v252
	v_mul_f32_e32 v237, v244, v237
	v_mul_f32_e32 v244, v248, v253
	s_waitcnt lgkmcnt(0)
	v_mfma_f32_16x16x32_bf16 v[116:119], v[116:119], v[238:241], v[128:131]
	ds_read_b32 v128, v203
	s_nop 2
	v_mul_f32_e32 v245, v245, v250
	v_mul_f32_e32 v182, v249, v182
	v_cvt_pk_bf16_f32 v124, v139, v170
	v_cvt_pk_bf16_f32 v125, v237, v245
	s_waitcnt lgkmcnt(0)
; __device__ __forceinline__ void phase_ssd(const Params& p, uchar* sm, int j, bf16_t* zx, const float* dtraw, float* ssqb) {
;     ...
;                 const float dec = e1L[rl * 64 + 63];
; #pragma unroll
;                 for (int n = 0; n < 8; ++n) {
;                     st[n] *= dec;
; #pragma unroll
;                     for (int ks = 0; ks < 2; ++ks) { const bf16x8 afr = *(const bf16x8*)(sm + L_BT + (n * 16 + l15) * RS_T + (((ks * 16 + quad * 4) ^ (4 * n)) * 4));
;                         st[n] = __builtin_amdgcn_mfma_f32_16x16x32_bf16(afr, xdd[ks], st[n], 0, 0, 0); }
;                 }
;             }
;             if (c + 1 < 32) { load_raw(zc + 64 * LDZ + 2048 + colb, toff, false, 2 * lp, rb); load_raw(zc + 64 * LDZ + 2048 + colc, toff, false, 2 * lp, rc); }
	v_pk_mul_f32 v[74:75], v[74:75], v[128:129] op_sel_hi:[1,0]
	v_pk_mul_f32 v[72:73], v[72:73], v[128:129] op_sel_hi:[1,0]
	v_add_u32_e32 v129, v205, v188
	ds_read_b128 v[130:133], v129 offset:34816
	ds_read_b128 v[238:241], v129 offset:34880
	ds_read_b128 v[246:249], v221 offset:37120
	ds_read_b128 v[250:253], v221 offset:37184
	s_waitcnt lgkmcnt(3)
	v_mfma_f32_16x16x32_bf16 v[72:75], v[130:133], v[104:107], v[72:75]
	ds_read_b128 v[130:133], v222 offset:39424
	v_cvt_pk_bf16_f32 v126, v145, v243
	v_cvt_pk_bf16_f32 v127, v244, v182
	ds_read_b128 v[242:245], v222 offset:39488
	v_pk_mul_f32 v[78:79], v[78:79], v[128:129] op_sel_hi:[1,0]
	s_waitcnt lgkmcnt(4)
	v_mfma_f32_16x16x32_bf16 v[72:75], v[238:241], v[124:127], v[72:75]
	ds_read_b128 v[238:241], v223 offset:41728
	v_pk_mul_f32 v[76:77], v[76:77], v[128:129] op_sel_hi:[1,0]
	v_pk_mul_f32 v[66:67], v[66:67], v[128:129] op_sel_hi:[1,0]
	v_pk_mul_f32 v[64:65], v[64:65], v[128:129] op_sel_hi:[1,0]
	s_waitcnt lgkmcnt(4)
	v_mfma_f32_16x16x32_bf16 v[76:79], v[246:249], v[104:107], v[76:79]
	ds_read_b128 v[246:249], v223 offset:41792
	v_pk_mul_f32 v[70:71], v[70:71], v[128:129] op_sel_hi:[1,0]
	v_pk_mul_f32 v[68:69], v[68:69], v[128:129] op_sel_hi:[1,0]
	s_waitcnt lgkmcnt(4)
	v_mfma_f32_16x16x32_bf16 v[76:79], v[250:253], v[124:127], v[76:79]
	ds_read_b128 v[250:253], v129 offset:44096
	v_pk_mul_f32 v[94:95], v[94:95], v[128:129] op_sel_hi:[1,0]
	v_pk_mul_f32 v[92:93], v[92:93], v[128:129] op_sel_hi:[1,0]
	s_waitcnt lgkmcnt(4)
	v_mfma_f32_16x16x32_bf16 v[64:67], v[130:133], v[104:107], v[64:67]
	ds_read_b128 v[130:133], v129 offset:44032
	v_pk_mul_f32 v[82:83], v[82:83], v[128:129] op_sel_hi:[1,0]
	v_pk_mul_f32 v[80:81], v[80:81], v[128:129] op_sel_hi:[1,0]
	s_waitcnt lgkmcnt(4)
	v_mfma_f32_16x16x32_bf16 v[64:67], v[242:245], v[124:127], v[64:67]
	ds_read_b128 v[242:245], v221 offset:46400
	v_pk_mul_f32 v[86:87], v[86:87], v[128:129] op_sel_hi:[1,0]
	v_pk_mul_f32 v[84:85], v[84:85], v[128:129] op_sel_hi:[1,0]
	s_waitcnt lgkmcnt(4)
	v_mfma_f32_16x16x32_bf16 v[68:71], v[238:241], v[104:107], v[68:71]
	ds_read_b128 v[238:241], v221 offset:46336
	v_pk_mul_f32 v[90:91], v[90:91], v[128:129] op_sel_hi:[1,0]
	v_pk_mul_f32 v[88:89], v[88:89], v[128:129] op_sel_hi:[1,0]
	s_waitcnt lgkmcnt(4)
	v_mfma_f32_16x16x32_bf16 v[68:71], v[246:249], v[124:127], v[68:71]
	ds_read_b128 v[246:249], v222 offset:48704
	s_waitcnt lgkmcnt(4)
	v_mfma_f32_16x16x32_bf16 v[92:95], v[250:253], v[104:107], v[92:95]
	ds_read_b128 v[250:253], v222 offset:48640
	s_waitcnt lgkmcnt(4)
	v_mfma_f32_16x16x32_bf16 v[92:95], v[130:133], v[124:127], v[92:95]
	ds_read_b128 v[128:131], v223 offset:51008
	s_waitcnt lgkmcnt(3)
	v_mfma_f32_16x16x32_bf16 v[80:83], v[242:245], v[104:107], v[80:83]
	v_mfma_f32_16x16x32_bf16 v[80:83], v[238:241], v[124:127], v[80:83]
	ds_read_b128 v[240:243], v223 offset:50944
	s_waitcnt lgkmcnt(1)
	v_mfma_f32_16x16x32_bf16 v[84:87], v[246:249], v[104:107], v[84:87]
	v_mfma_f32_16x16x32_bf16 v[84:87], v[250:253], v[124:127], v[84:87]
	v_mfma_f32_16x16x32_bf16 v[88:91], v[128:131], v[104:107], v[88:91]
	s_waitcnt lgkmcnt(0)
	v_mfma_f32_16x16x32_bf16 v[88:91], v[240:243], v[124:127], v[88:91]
	s_cbranch_vccnz .Lssd_drain
	v_readlane_b32 s60, v254, 0
	v_readlane_b32 s66, v254, 6
	v_readlane_b32 s67, v254, 7
	v_readlane_b32 s61, v254, 1
	v_readlane_b32 s62, v254, 2
	v_lshl_add_u64 v[40:41], s[66:67], 0, v[176:177]
	v_add_co_u32_e32 v20, vcc, 0x64d6000, v40
	v_readlane_b32 s63, v254, 3
	s_nop 0
	v_addc_co_u32_e32 v21, vcc, 0, v41, vcc
	v_add_co_u32_e32 v28, vcc, 0x64d9000, v40
	v_readlane_b32 s64, v254, 4
	s_nop 0
	v_addc_co_u32_e32 v29, vcc, 0, v41, vcc
	v_add_co_u32_e32 v32, vcc, 0x64dc000, v40
	global_load_dwordx4 v[20:23], v[20:21], off offset:3712
	s_nop 0
	global_load_dwordx4 v[28:31], v[28:29], off offset:3840
	v_addc_co_u32_e32 v33, vcc, 0, v41, vcc
	v_add_co_u32_e32 v44, vcc, 0x64e0000, v40
	v_readlane_b32 s65, v254, 5
	s_nop 0
	v_addc_co_u32_e32 v45, vcc, 0, v41, vcc
	v_add_co_u32_e32 v60, vcc, 0x64e3000, v40
	global_load_dwordx4 v[32:35], v[32:33], off offset:3968
	s_nop 0
	global_load_dwordx4 v[36:39], v[44:45], off
	v_addc_co_u32_e32 v61, vcc, 0, v41, vcc
	v_add_co_u32_e32 v46, vcc, 0x64d7000, v40
	s_nop 1
	v_addc_co_u32_e32 v47, vcc, 0, v41, vcc
	v_add_co_u32_e32 v42, vcc, 0x64da000, v40
	s_nop 1
	v_addc_co_u32_e32 v43, vcc, 0, v41, vcc
	v_add_co_u32_e32 v40, vcc, 0x64dd000, v40
	s_nop 1
	v_addc_co_u32_e32 v41, vcc, 0, v41, vcc
	global_load_dwordx4 v[48:51], v[42:43], off offset:1792
	global_load_dwordx4 v[52:55], v[40:41], off offset:1920
	s_nop 0
	global_load_dwordx4 v[40:43], v[60:61], off offset:128
	global_load_dwordx4 v[56:59], v[44:45], off offset:2048
	s_nop 0
	global_load_dwordx4 v[44:47], v[46:47], off offset:1664
	s_nop 0
	global_load_dwordx4 v[60:63], v[60:61], off offset:2176
; __device__ __forceinline__ u32x4 pack8(const float (&o)[8]) { u32x4 r; r.x = pk2(o[0], o[1]); r.y = pk2(o[2], o[3]); r.z = pk2(o[4], o[5]); r.w = pk2(o[6], o[7]); return r; }
; __device__ __forceinline__ float silu_f(float v) { return v * __builtin_amdgcn_rcpf(1.f + __expf(-v)); }
; __device__ __forceinline__ void phase_ssd(const Params& p, uchar* sm, int j, bf16_t* zx, const float* dtraw, float* ssqb) {
;     ...
;             __syncthreads();
; #pragma unroll
;             for (int m = 0; m < 4; ++m)
; #pragma unroll
;                 for (int r = 0; r < 4; ++r) *(float*)(sm + (m * 16 + quad * 4 + r) * RS_Y + (chl + l15) * 4) = yacc[m][r];
;             __syncthreads();
;             {
;                 float zf[8], o[8], xf[8];
;                 const f32x4 y0 = *(const f32x4*)(sm + (2 * lp) * RS_Y + c8 * 32), y1 = *(const f32x4*)(sm + (2 * lp) * RS_Y + c8 * 32 + 16);
;                 unpack8(z0, zf); unpack8(xp0, xf);
; #pragma unroll
;                 for (int i = 0; i < 4; ++i) { o[i] = (y0[i] + dskip * xf[i]) * silu_f(zf[i]); o[4 + i] = (y1[i] + dskip * xf[4 + i]) * silu_f(zf[4 + i]); }
;                 *(u32x4*)(zc + colx + toff) = pack8(o);
;                 float q0 = 0.f;
; #pragma unroll
;                 for (int i = 0; i < 8; ++i) q0 += o[i] * o[i];
;                 const f32x4 y2 = *(const f32x4*)(sm + (2 * lp + 1) * RS_Y + c8 * 32), y3 = *(const f32x4*)(sm + (2 * lp + 1) * RS_Y + c8 * 32 + 16);
;                 unpack8(z1, zf); unpack8(xp1, xf);
; #pragma unroll
;                 for (int i = 0; i < 4; ++i) { o[i] = (y2[i] + dskip * xf[i]) * silu_f(zf[i]); o[4 + i] = (y3[i] + dskip * xf[4 + i]) * silu_f(zf[4 + i]); }
;                 *(u32x4*)(zc + colx + LDZ + toff) = pack8(o);
.LBB0_479:
	v_add_u32_e32 v104, 0x400, v224
	s_barrier
	ds_write2_b32 v104, v110, v111 offset0:8 offset1:140
	v_add_u32_e32 v104, 0x2000, v224
	ds_write2_b32 v104, v112, v113 offset0:64 offset1:196
	v_add_u32_e32 v104, 0x2400, v224
	ds_write2_b32 v104, v114, v115 offset0:72 offset1:204
	v_add_u32_e32 v104, 0x4200, v224
	ds_write2_b32 v104, v120, v121 offset1:132
	v_add_u32_e32 v104, 0x4600, v224
	ds_write2_b32 v104, v122, v123 offset0:8 offset1:140
	v_add_u32_e32 v104, 0x6200, v224
	ds_write2_b32 v104, v116, v117 offset0:64 offset1:196
	v_add_u32_e32 v104, 0x6600, v224
	s_waitcnt vmcnt(11)
	v_lshlrev_b32_e32 v112, 16, v100
	ds_write2_b32 v104, v118, v119 offset0:72 offset1:204
	v_mul_f32_e32 v104, 0xbfb8aa3b, v112
	v_exp_f32_e32 v114, v104
	ds_write2_b32 v224, v108, v109 offset1:132
	s_waitcnt lgkmcnt(0)
	s_barrier
	ds_read_b128 v[104:107], v225
	ds_read_b128 v[108:111], v225 offset:16
	v_add_f32_e32 v114, 1.0, v114
	v_rcp_f32_e32 v170, v114
	v_lshlrev_b32_e32 v114, 16, v102
	v_lshlrev_b32_e32 v113, 16, v235
	v_mul_f32_e32 v115, 0xbfb8aa3b, v114
	v_exp_f32_e32 v115, v115
	v_pk_mul_f32 v[112:113], v[170:171], v[112:113]
	s_waitcnt lgkmcnt(1)
	v_add_f32_e32 v104, v113, v104
	v_mul_f32_e32 v116, v112, v104
	v_and_b32_e32 v112, 0xffff0000, v100
	v_mul_f32_e32 v100, 0xbfb8aa3b, v112
	v_add_f32_e32 v104, 1.0, v115
	v_exp_f32_e32 v100, v100
	v_rcp_f32_e32 v170, v104
	v_lshlrev_b32_e32 v115, 16, v236
	v_and_b32_e32 v104, 0xffff0000, v102
	v_add_f32_e32 v100, 1.0, v100
	v_pk_mul_f32 v[114:115], v[170:171], v[114:115]
	v_rcp_f32_e32 v170, v100
	v_mul_f32_e32 v100, 0xbfb8aa3b, v104
	v_exp_f32_e32 v100, v100
	v_and_b32_e32 v113, 0xffff0000, v235
	s_waitcnt lgkmcnt(0)
	v_add_f32_e32 v108, v115, v108
	v_pk_mul_f32 v[112:113], v[170:171], v[112:113]
	v_add_f32_e32 v100, 1.0, v100
	v_mul_f32_e32 v114, v114, v108
	v_rcp_f32_e32 v170, v100
	v_add_f32_e32 v100, v113, v105
	v_lshlrev_b32_e32 v108, 16, v101
	v_mul_f32_e32 v112, v112, v100
	v_mul_f32_e32 v100, 0xbfb8aa3b, v108
	v_exp_f32_e32 v100, v100
	v_and_b32_e32 v105, 0xffff0000, v236
	v_pk_mul_f32 v[104:105], v[170:171], v[104:105]
	v_mul_f32_e32 v120, v112, v112
	v_add_f32_e32 v100, 1.0, v100
	v_add_f32_e32 v102, v105, v109
	v_rcp_f32_e32 v170, v100
	v_lshlrev_b32_e32 v100, 16, v103
	v_mul_f32_e32 v113, v104, v102
	v_mul_f32_e32 v102, 0xbfb8aa3b, v100
	v_exp_f32_e32 v102, v102
	v_lshlrev_b32_e32 v109, 16, v233
	v_pk_mul_f32 v[104:105], v[170:171], v[108:109]
	s_waitcnt vmcnt(10)
	v_lshlrev_b32_e32 v108, 16, v96
	v_add_f32_e32 v102, 1.0, v102
	v_rcp_f32_e32 v170, v102
	v_and_b32_e32 v102, 0xffff0000, v101
	v_add_f32_e32 v105, v105, v106
	v_mul_f32_e32 v101, 0xbfb8aa3b, v102
	v_mul_f32_e32 v115, v104, v105
	v_exp_f32_e32 v104, v101
	v_lshlrev_b32_e32 v101, 16, v234
	v_pk_mul_f32 v[100:101], v[170:171], v[100:101]
	v_lshlrev_b32_e32 v109, 16, v231
	v_add_f32_e32 v104, 1.0, v104
	v_rcp_f32_e32 v170, v104
	v_and_b32_e32 v104, 0xffff0000, v103
	v_mul_f32_e32 v103, 0xbfb8aa3b, v104
	ds_read_b128 v[124:127], v226
	v_exp_f32_e32 v105, v103
	v_add_f32_e32 v101, v101, v110
	v_and_b32_e32 v103, 0xffff0000, v233
	v_mul_f32_e32 v117, v100, v101
	v_pk_mul_f32 v[100:101], v[170:171], v[102:103]
	v_add_f32_e32 v102, 1.0, v105
	v_rcp_f32_e32 v170, v102
	v_add_f32_e32 v101, v101, v107
	v_and_b32_e32 v105, 0xffff0000, v234
	v_mul_f32_e32 v118, v100, v101
	v_pk_mul_f32 v[100:101], v[170:171], v[104:105]
	v_fmac_f32_e32 v120, v116, v116
	v_add_f32_e32 v101, v101, v111
	v_mul_f32_e32 v119, v100, v101
	v_mul_f32_e32 v100, 0xbfb8aa3b, v108
	v_exp_f32_e32 v110, v100
	ds_read_b128 v[104:107], v226 offset:16
	v_fmac_f32_e32 v120, v115, v115
	v_fmac_f32_e32 v120, v118, v118
	v_add_f32_e32 v110, 1.0, v110
	v_rcp_f32_e32 v170, v110
	v_lshlrev_b32_e32 v110, 16, v98
	v_mul_f32_e32 v111, 0xbfb8aa3b, v110
	v_exp_f32_e32 v111, v111
	v_pk_mul_f32 v[108:109], v[170:171], v[108:109]
	v_fmac_f32_e32 v120, v114, v114
	s_waitcnt lgkmcnt(1)
	v_add_f32_e32 v124, v109, v124
	v_mul_f32_e32 v121, v108, v124
	v_and_b32_e32 v108, 0xffff0000, v96
	v_mul_f32_e32 v96, 0xbfb8aa3b, v108
	v_add_f32_e32 v100, 1.0, v111
	v_exp_f32_e32 v96, v96
	v_rcp_f32_e32 v170, v100
	v_lshlrev_b32_e32 v111, 16, v232
	v_and_b32_e32 v100, 0xffff0000, v98
	v_add_f32_e32 v96, 1.0, v96
	v_pk_mul_f32 v[110:111], v[170:171], v[110:111]
	v_rcp_f32_e32 v170, v96
	v_mul_f32_e32 v96, 0xbfb8aa3b, v100
	v_exp_f32_e32 v96, v96
	v_and_b32_e32 v109, 0xffff0000, v231
	s_waitcnt lgkmcnt(0)
; __device__ __forceinline__ u32x4 pack8(const float (&o)[8]) { u32x4 r; r.x = pk2(o[0], o[1]); r.y = pk2(o[2], o[3]); r.z = pk2(o[4], o[5]); r.w = pk2(o[6], o[7]); return r; }
; __device__ __forceinline__ float silu_f(float v) { return v * __builtin_amdgcn_rcpf(1.f + __expf(-v)); }
; __device__ __forceinline__ void phase_ssd(const Params& p, uchar* sm, int j, bf16_t* zx, const float* dtraw, float* ssqb) {
;     ...
;                 for (int i = 0; i < 4; ++i) { o[i] = (y2[i] + dskip * xf[i]) * silu_f(zf[i]); o[4 + i] = (y3[i] + dskip * xf[4 + i]) * silu_f(zf[4 + i]); }
;                 *(u32x4*)(zc + colx + LDZ + toff) = pack8(o);
;                 float q1 = 0.f;
; #pragma unroll
;                 for (int i = 0; i < 8; ++i) q1 += o[i] * o[i];
; #pragma unroll
;                 for (int sft = 1; sft < 16; sft <<= 1) { q0 += __shfl_xor(q0, sft); q1 += __shfl_xor(q1, sft); }
;                 if (c8 == 0) { float* sq = ssqb + (size_t)(zrow0 + 2 * lp) * 16 + g * 2 + hp; sq[0] = q0; sq[16] = q1; }
	v_add_f32_e32 v104, v111, v104
	v_pk_mul_f32 v[108:109], v[170:171], v[108:109]
	v_add_f32_e32 v96, 1.0, v96
	v_mul_f32_e32 v110, v110, v104
	v_rcp_f32_e32 v170, v96
	v_add_f32_e32 v96, v109, v125
	v_lshlrev_b32_e32 v104, 16, v97
	v_mul_f32_e32 v108, v108, v96
	v_mul_f32_e32 v96, 0xbfb8aa3b, v104
	v_exp_f32_e32 v96, v96
	v_and_b32_e32 v101, 0xffff0000, v232
	v_pk_mul_f32 v[100:101], v[170:171], v[100:101]
	v_fmac_f32_e32 v120, v113, v113
	v_add_f32_e32 v96, 1.0, v96
	v_add_f32_e32 v98, v101, v105
	v_rcp_f32_e32 v170, v96
	v_lshlrev_b32_e32 v96, 16, v99
	v_mul_f32_e32 v109, v100, v98
	v_mul_f32_e32 v98, 0xbfb8aa3b, v96
	v_exp_f32_e32 v98, v98
	v_lshlrev_b32_e32 v105, 16, v229
	v_pk_mul_f32 v[100:101], v[170:171], v[104:105]
	v_fmac_f32_e32 v120, v117, v117
	v_add_f32_e32 v98, 1.0, v98
	v_rcp_f32_e32 v170, v98
	v_and_b32_e32 v98, 0xffff0000, v97
	v_add_f32_e32 v101, v101, v126
	v_mul_f32_e32 v97, 0xbfb8aa3b, v98
	v_mul_f32_e32 v102, v100, v101
	v_exp_f32_e32 v100, v97
	v_lshlrev_b32_e32 v97, 16, v230
	v_pk_mul_f32 v[96:97], v[170:171], v[96:97]
	v_fmac_f32_e32 v120, v119, v119
	v_add_f32_e32 v100, 1.0, v100
	v_rcp_f32_e32 v170, v100
	v_and_b32_e32 v100, 0xffff0000, v99
	v_mul_f32_e32 v99, 0xbfb8aa3b, v100
	v_exp_f32_e32 v101, v99
	v_add_f32_e32 v97, v97, v106
	v_and_b32_e32 v99, 0xffff0000, v229
	v_mul_f32_e32 v104, v96, v97
	v_pk_mul_f32 v[96:97], v[170:171], v[98:99]
	v_add_f32_e32 v98, 1.0, v101
	v_rcp_f32_e32 v170, v98
	v_add_f32_e32 v97, v97, v127
	v_and_b32_e32 v101, 0xffff0000, v230
	v_mul_f32_e32 v103, v96, v97
	v_pk_mul_f32 v[96:97], v[170:171], v[100:101]
	s_nop 0
	v_add_f32_e32 v97, v97, v107
	v_mul_f32_e32 v105, v96, v97
	v_mul_f32_e32 v96, v108, v108
	v_fmac_f32_e32 v96, v121, v121
	v_fmac_f32_e32 v96, v102, v102
	v_fmac_f32_e32 v96, v103, v103
	v_and_b32_e32 v97, 64, v137
	v_fmac_f32_e32 v96, v110, v110
	v_add_u32_e32 v101, 64, v97
	v_xor_b32_e32 v97, 1, v137
	v_fmac_f32_e32 v96, v109, v109
	v_cmp_lt_i32_e32 vcc, v97, v101
	v_fmac_f32_e32 v96, v104, v104
	v_fmac_f32_e32 v96, v105, v105
	v_cndmask_b32_e32 v97, v137, v97, vcc
	v_lshlrev_b32_e32 v97, 2, v97
	ds_bpermute_b32 v98, v97, v120
	ds_bpermute_b32 v97, v97, v96
	s_waitcnt lgkmcnt(0)
	v_add_f32_e32 v99, v120, v98
	v_add_f32_e32 v100, v96, v97
	v_xor_b32_e32 v96, 2, v137
	v_cmp_lt_i32_e32 vcc, v96, v101
	v_cvt_pk_bf16_f32 v98, v114, v113
	v_cvt_pk_bf16_f32 v97, v115, v118
	s_nop 1
	v_cndmask_b32_e32 v96, v137, v96, vcc
	v_lshlrev_b32_e32 v96, 2, v96
	ds_bpermute_b32 v106, v96, v99
	ds_bpermute_b32 v107, v96, v100
	v_cvt_pk_bf16_f32 v96, v116, v112
	s_waitcnt lgkmcnt(1)
	v_add_f32_e32 v106, v99, v106
	v_xor_b32_e32 v99, 4, v137
	v_cmp_lt_i32_e32 vcc, v99, v101
	s_waitcnt lgkmcnt(0)
	v_add_f32_e32 v107, v100, v107
	v_cvt_pk_bf16_f32 v100, v121, v108
	v_cndmask_b32_e32 v99, v137, v99, vcc
	v_lshlrev_b32_e32 v99, 2, v99
	ds_bpermute_b32 v111, v99, v106
	ds_bpermute_b32 v112, v99, v107
	v_cvt_pk_bf16_f32 v99, v117, v119
	global_store_dwordx4 v[180:181], v[96:99], off
	s_nop 1
	v_xor_b32_e32 v98, 8, v137
	v_cmp_lt_i32_e32 vcc, v98, v101
	s_waitcnt lgkmcnt(0)
	v_add_f32_e32 v96, v106, v111
	v_add_f32_e32 v97, v107, v112
	v_cndmask_b32_e32 v98, v137, v98, vcc
	v_lshlrev_b32_e32 v99, 2, v98
	ds_bpermute_b32 v98, v99, v96
	ds_bpermute_b32 v99, v99, v97
	v_cvt_pk_bf16_f32 v101, v102, v103
	v_cvt_pk_bf16_f32 v102, v110, v109
	v_cvt_pk_bf16_f32 v103, v104, v105
	global_store_dwordx4 v[178:179], v[100:103], off
	s_and_saveexec_b64 s[0:1], s[24:25]
	s_cbranch_execz .LBB0_465
	v_readlane_b32 s60, v254, 0
	v_readlane_b32 s66, v254, 6
	v_readlane_b32 s67, v254, 7
	s_waitcnt lgkmcnt(0)
	v_add_f32_e32 v99, v97, v99
	v_add_f32_e32 v98, v96, v98
	v_lshl_add_u64 v[96:97], s[66:67], 0, v[172:173]
	v_add_co_u32_e32 v96, vcc, 0x1ec1c000, v96
	v_readlane_b32 s61, v254, 1
	s_nop 0
	v_addc_co_u32_e32 v97, vcc, 0, v97, vcc
	v_readlane_b32 s62, v254, 2
	v_readlane_b32 s63, v254, 3
	v_readlane_b32 s64, v254, 4
	v_readlane_b32 s65, v254, 5
	global_store_dword v[96:97], v98, off
	global_store_dword v[96:97], v99, off offset:64
	s_branch .LBB0_465

; template <class Epi, bool ALIGN_EPI = PG8_ALIGN, bool SP2 = PG8_SP2>
; __device__ __forceinline__ void gemm_phase(LAS uchar* lds, const Gemm g, const StaticOrder& S, const Epi& E) {
;     ...
;     f32x4 acc[2][2][4][2];
; #pragma unroll
;     for (int a = 0; a < 2; ++a)
; #pragma unroll
;         for (int b = 0; b < 2; ++b)
; #pragma unroll
;             for (int m = 0; m < 4; ++m)
; #pragma unroll
;                 for (int n = 0; n < 2; ++n) acc[a][b][m][n] = (f32x4){0.f, 0.f, 0.f, 0.f};
.LBB0_668:
	s_add_u32 s36, s14, 0x100
	v_mov_b32_e32 v129, 0x20010
	s_addc_u32 s37, s15, 0
	s_mov_b32 s38, -2
	ds_read_b128 v[2:5], v129
	ds_read_b128 v[6:9], v129
	ds_read_b128 v[10:13], v129
	ds_read_b128 v[14:17], v129
	ds_read_b128 v[18:21], v129
	ds_read_b128 v[22:25], v129
	ds_read_b128 v[26:29], v129
	ds_read_b128 v[30:33], v129
	ds_read_b128 v[34:37], v129
	ds_read_b128 v[38:41], v129
	ds_read_b128 v[42:45], v129
	ds_read_b128 v[46:49], v129
	ds_read_b128 v[50:53], v129
	ds_read_b128 v[54:57], v129
	ds_read_b128 v[58:61], v129
	ds_read_b128 v[62:65], v129
	ds_read_b128 v[66:69], v129
	ds_read_b128 v[70:73], v129
	ds_read_b128 v[74:77], v129
	ds_read_b128 v[78:81], v129
	ds_read_b128 v[82:85], v129
	ds_read_b128 v[86:89], v129
	ds_read_b128 v[90:93], v129
	ds_read_b128 v[94:97], v129
	ds_read_b128 v[98:101], v129
	ds_read_b128 v[102:105], v129
	ds_read_b128 v[106:109], v129
	ds_read_b128 v[110:113], v129
	ds_read_b128 v[114:117], v129
	ds_read_b128 v[118:121], v129
	ds_read_b128 v[122:125], v129
	ds_read_b128 v[126:129], v129

; template <class Epi, bool ALIGN_EPI = PG8_ALIGN, bool SP2 = PG8_SP2>
; __device__ __forceinline__ void gemm_phase(LAS uchar* lds, const Gemm g, const StaticOrder& S, const Epi& E) {
;     ...
;     f32x4 acc[2][2][4][2];
; #pragma unroll
;     for (int a = 0; a < 2; ++a)
; #pragma unroll
;         for (int b = 0; b < 2; ++b)
; #pragma unroll
;             for (int m = 0; m < 4; ++m)
; #pragma unroll
;                 for (int n = 0; n < 2; ++n) acc[a][b][m][n] = (f32x4){0.f, 0.f, 0.f, 0.f};
.LBB0_1142:
	s_add_u32 s38, s16, 0x100
	v_mov_b32_e32 v129, 0x20010
	s_addc_u32 s39, s17, 0
	s_mov_b32 s40, -2
	ds_read_b128 v[2:5], v129
	ds_read_b128 v[6:9], v129
	ds_read_b128 v[10:13], v129
	ds_read_b128 v[14:17], v129
	ds_read_b128 v[18:21], v129
	ds_read_b128 v[22:25], v129
	ds_read_b128 v[26:29], v129
	ds_read_b128 v[30:33], v129
	ds_read_b128 v[34:37], v129
	ds_read_b128 v[38:41], v129
	ds_read_b128 v[42:45], v129
	ds_read_b128 v[46:49], v129
	ds_read_b128 v[50:53], v129
	ds_read_b128 v[54:57], v129
	ds_read_b128 v[58:61], v129
	ds_read_b128 v[62:65], v129
	ds_read_b128 v[66:69], v129
	ds_read_b128 v[70:73], v129
	ds_read_b128 v[74:77], v129
	ds_read_b128 v[78:81], v129
	ds_read_b128 v[82:85], v129
	ds_read_b128 v[86:89], v129
	ds_read_b128 v[90:93], v129
	ds_read_b128 v[94:97], v129
	ds_read_b128 v[98:101], v129
	ds_read_b128 v[102:105], v129
	ds_read_b128 v[106:109], v129
	ds_read_b128 v[110:113], v129
	ds_read_b128 v[114:117], v129
	ds_read_b128 v[118:121], v129
	ds_read_b128 v[122:125], v129
	ds_read_b128 v[126:129], v129
